# adaLN k-loop keeps 16 weight-row loads in flight (4-deep pipeline); grid-barrier census loads issued together
# baseline (speedup 1.0000x reference)
.LBB0_29:
	global_load_dword v3, v1, s[80:81] sc1
	s_waitcnt lgkmcnt(0)
	global_load_dword v0, v1, s[48:49] sc1
	global_load_dword v2, v1, s[94:95] sc1
	s_mov_b64 s[6:7], -1
	s_mov_b64 s[20:21], -1
	v_readlane_b32 s2, v251, 15
	v_readlane_b32 s3, v251, 16
	s_nop 1
	v_mov_b32_e32 v148, s2
	v_mov_b32_e32 v149, s3
	global_load_dword v4, v[148:149], off sc1
	v_readlane_b32 s2, v251, 17
	v_readlane_b32 s3, v251, 18
	s_nop 1
	v_mov_b32_e32 v150, s2
	v_mov_b32_e32 v151, s3
	global_load_dword v5, v[150:151], off sc1
	v_readlane_b32 s2, v251, 19
	v_readlane_b32 s3, v251, 20
	s_nop 1
	v_mov_b32_e32 v152, s2
	v_mov_b32_e32 v153, s3
	global_load_dword v6, v[152:153], off sc1
	v_readlane_b32 s2, v251, 21
	v_readlane_b32 s3, v251, 22
	s_nop 1
	v_mov_b32_e32 v154, s2
	v_mov_b32_e32 v155, s3
	global_load_dword v7, v[154:155], off sc1
	v_readlane_b32 s2, v251, 23
	v_readlane_b32 s3, v251, 24
	s_nop 1
	v_mov_b32_e32 v156, s2
	v_mov_b32_e32 v157, s3
	global_load_dword v8, v[156:157], off sc1
	v_readlane_b32 s2, v251, 25
	v_readlane_b32 s3, v251, 26
	s_nop 1
	v_mov_b32_e32 v158, s2
	v_mov_b32_e32 v159, s3
	global_load_dword v9, v[158:159], off sc1
	v_readlane_b32 s2, v251, 27
	v_readlane_b32 s3, v251, 28
	s_nop 1
	v_mov_b32_e32 v160, s2
	v_mov_b32_e32 v161, s3
	global_load_dword v10, v[160:161], off sc1
	v_readlane_b32 s2, v251, 29
	v_readlane_b32 s3, v251, 30
	s_nop 1
	v_mov_b32_e32 v162, s2
	v_mov_b32_e32 v163, s3
	global_load_dword v11, v[162:163], off sc1
	v_readlane_b32 s2, v251, 31
	v_readlane_b32 s3, v251, 32
	s_nop 1
	v_mov_b32_e32 v164, s2
	v_mov_b32_e32 v165, s3
	global_load_dword v12, v[164:165], off sc1
	v_readlane_b32 s2, v251, 33
	v_readlane_b32 s3, v251, 34
	s_nop 1
	v_mov_b32_e32 v166, s2
	v_mov_b32_e32 v167, s3
	global_load_dword v13, v[166:167], off sc1
	v_readlane_b32 s2, v251, 35
	v_readlane_b32 s3, v251, 36
	s_nop 1
	v_mov_b32_e32 v168, s2
	v_mov_b32_e32 v169, s3
	global_load_dword v14, v[168:169], off sc1
	v_readlane_b32 s2, v251, 37
	v_readlane_b32 s3, v251, 38
	s_nop 1
	v_mov_b32_e32 v170, s2
	v_mov_b32_e32 v171, s3
	global_load_dword v15, v[170:171], off sc1
	v_readlane_b32 s2, v251, 39
	v_readlane_b32 s3, v251, 40
	s_nop 1
	v_mov_b32_e32 v172, s2
	v_mov_b32_e32 v173, s3
	global_load_dword v16, v[172:173], off sc1
	s_waitcnt vmcnt(0)
	v_add_u32_e32 v17, v0, v3
	v_add_u32_e32 v17, v17, v2
	v_add_u32_e32 v17, v17, v4
	v_add_u32_e32 v17, v17, v5
	v_add_u32_e32 v17, v17, v6
	v_add_u32_e32 v17, v17, v7
	v_add_u32_e32 v17, v17, v8
	v_add_u32_e32 v17, v17, v9
	v_add_u32_e32 v17, v17, v10
	v_add_u32_e32 v17, v17, v11
	v_add_u32_e32 v17, v17, v12
	v_add_u32_e32 v17, v17, v13
	v_add_u32_e32 v17, v17, v14
	v_add_u32_e32 v17, v17, v15
	v_add_u32_e32 v17, v17, v16
	v_cmp_eq_u32_e32 vcc, s97, v17
	s_cbranch_vccnz .LBB0_28
	s_and_b32 s3, s0, 0xff
	s_cmp_eq_u32 s3, 0
	s_mov_b64 s[22:23], -1
	s_sleep 1
	s_cbranch_scc1 .LBB0_33
	s_and_b64 vcc, exec, s[22:23]
	s_cbranch_vccz .LBB0_28

.LBB0_1533:
	v_mov_b32_e32 v200, 0x6000
	v_mov_b32_e32 v201, 0
	v_mov_b32_e32 v202, 0xc000
	v_mov_b32_e32 v203, 0
	v_mov_b32_e32 v204, 0x12000
	v_mov_b32_e32 v205, 0
	v_lshl_add_u64 v[196:197], v[74:75], 0, s[6:7]
	global_load_dwordx4 v[82:85], v[196:197], off
	v_lshl_add_u64 v[198:199], v[196:197], 0, v[200:201]
	global_load_dwordx4 v[86:89], v[198:199], off
	v_lshl_add_u64 v[198:199], v[196:197], 0, v[202:203]
	global_load_dwordx4 v[90:93], v[198:199], off
	v_lshl_add_u64 v[198:199], v[196:197], 0, v[204:205]
	global_load_dwordx4 v[94:97], v[198:199], off
	s_add_u32 s6, s6, 0x18000
	s_addc_u32 s7, s7, 0
	v_lshl_add_u64 v[196:197], v[74:75], 0, s[6:7]
	global_load_dwordx4 v[148:151], v[196:197], off
	v_lshl_add_u64 v[198:199], v[196:197], 0, v[200:201]
	global_load_dwordx4 v[152:155], v[198:199], off
	v_lshl_add_u64 v[198:199], v[196:197], 0, v[202:203]
	global_load_dwordx4 v[156:159], v[198:199], off
	v_lshl_add_u64 v[198:199], v[196:197], 0, v[204:205]
	global_load_dwordx4 v[160:163], v[198:199], off
	s_add_u32 s6, s6, 0x18000
	s_addc_u32 s7, s7, 0
	v_lshl_add_u64 v[196:197], v[74:75], 0, s[6:7]
	global_load_dwordx4 v[164:167], v[196:197], off
	v_lshl_add_u64 v[198:199], v[196:197], 0, v[200:201]
	global_load_dwordx4 v[168:171], v[198:199], off
	v_lshl_add_u64 v[198:199], v[196:197], 0, v[202:203]
	global_load_dwordx4 v[172:175], v[198:199], off
	v_lshl_add_u64 v[198:199], v[196:197], 0, v[204:205]
	global_load_dwordx4 v[176:179], v[198:199], off
	s_add_u32 s6, s6, 0x18000
	s_addc_u32 s7, s7, 0
	v_lshl_add_u64 v[196:197], v[74:75], 0, s[6:7]
	global_load_dwordx4 v[180:183], v[196:197], off
	v_lshl_add_u64 v[198:199], v[196:197], 0, v[200:201]
	global_load_dwordx4 v[184:187], v[198:199], off
	v_lshl_add_u64 v[198:199], v[196:197], 0, v[202:203]
	global_load_dwordx4 v[188:191], v[198:199], off
	v_lshl_add_u64 v[198:199], v[196:197], 0, v[204:205]
	global_load_dwordx4 v[192:195], v[198:199], off
	s_add_u32 s6, s6, 0x18000
	s_addc_u32 s7, s7, 0
.Ladaln_round:
	ds_read_b128 v[38:41], v80 offset:4096
	ds_read_b128 v[42:45], v80 offset:8192
	ds_read_b128 v[46:49], v80
	ds_read_b128 v[50:53], v80 offset:32768
	ds_read_b128 v[58:61], v80 offset:12288
	ds_read_b128 v[54:57], v80 offset:16384
	ds_read_b128 v[66:69], v80 offset:20480
	ds_read_b128 v[62:65], v80 offset:24576
	ds_read_b128 v[70:73], v80 offset:28672
	s_waitcnt lgkmcnt(6)
	v_mov_b32_e32 v76, v49
	v_mov_b32_e32 v98, v41
	v_mov_b32_e32 v100, v45
	s_waitcnt lgkmcnt(4)
	v_mov_b32_e32 v102, v61
	s_waitcnt lgkmcnt(3)
	v_mov_b32_e32 v104, v57
	s_waitcnt lgkmcnt(2)
	v_mov_b32_e32 v106, v69
	s_waitcnt lgkmcnt(1)
	v_mov_b32_e32 v108, v65
	s_waitcnt lgkmcnt(0)
	v_mov_b32_e32 v110, v73
	v_mov_b32_e32 v112, v53
	v_add_u32_e32 v80, 16, v80
	s_waitcnt vmcnt(15)
	v_pk_fma_f32 v[36:37], v[84:85], v[46:47], v[36:37] op_sel_hi:[1,0,1]
	v_pk_fma_f32 v[34:35], v[82:83], v[46:47], v[34:35] op_sel_hi:[1,0,1]
	v_pk_fma_f32 v[32:33], v[84:85], v[38:39], v[32:33] op_sel_hi:[1,0,1]
	v_pk_fma_f32 v[30:31], v[82:83], v[38:39], v[30:31] op_sel_hi:[1,0,1]
	v_pk_fma_f32 v[28:29], v[84:85], v[42:43], v[28:29] op_sel_hi:[1,0,1]
	v_pk_fma_f32 v[26:27], v[82:83], v[42:43], v[26:27] op_sel_hi:[1,0,1]
	v_pk_fma_f32 v[24:25], v[84:85], v[58:59], v[24:25] op_sel_hi:[1,0,1]
	v_pk_fma_f32 v[22:23], v[82:83], v[58:59], v[22:23] op_sel_hi:[1,0,1]
	v_pk_fma_f32 v[20:21], v[84:85], v[54:55], v[20:21] op_sel_hi:[1,0,1]
	v_pk_fma_f32 v[18:19], v[82:83], v[54:55], v[18:19] op_sel_hi:[1,0,1]
	v_pk_fma_f32 v[16:17], v[84:85], v[66:67], v[16:17] op_sel_hi:[1,0,1]
	v_pk_fma_f32 v[14:15], v[82:83], v[66:67], v[14:15] op_sel_hi:[1,0,1]
	v_pk_fma_f32 v[12:13], v[84:85], v[62:63], v[12:13] op_sel_hi:[1,0,1]
	v_pk_fma_f32 v[10:11], v[82:83], v[62:63], v[10:11] op_sel_hi:[1,0,1]
	v_pk_fma_f32 v[8:9], v[84:85], v[70:71], v[8:9] op_sel_hi:[1,0,1]
	v_pk_fma_f32 v[6:7], v[82:83], v[70:71], v[6:7] op_sel_hi:[1,0,1]
	v_pk_fma_f32 v[4:5], v[84:85], v[50:51], v[4:5] op_sel_hi:[1,0,1]
	v_pk_fma_f32 v[2:3], v[82:83], v[50:51], v[2:3] op_sel_hi:[1,0,1]
	s_waitcnt vmcnt(14)
	v_pk_fma_f32 v[34:35], v[86:87], v[46:47], v[34:35] op_sel:[0,1,0]
	v_pk_fma_f32 v[36:37], v[88:89], v[46:47], v[36:37] op_sel:[0,1,0]
	v_pk_fma_f32 v[30:31], v[86:87], v[38:39], v[30:31] op_sel:[0,1,0]
	v_pk_fma_f32 v[32:33], v[88:89], v[38:39], v[32:33] op_sel:[0,1,0]
	v_pk_fma_f32 v[26:27], v[86:87], v[42:43], v[26:27] op_sel:[0,1,0]
	v_pk_fma_f32 v[28:29], v[88:89], v[42:43], v[28:29] op_sel:[0,1,0]
	v_pk_fma_f32 v[22:23], v[86:87], v[58:59], v[22:23] op_sel:[0,1,0]
	v_pk_fma_f32 v[24:25], v[88:89], v[58:59], v[24:25] op_sel:[0,1,0]
	v_pk_fma_f32 v[18:19], v[86:87], v[54:55], v[18:19] op_sel:[0,1,0]
	v_pk_fma_f32 v[20:21], v[88:89], v[54:55], v[20:21] op_sel:[0,1,0]
	v_pk_fma_f32 v[14:15], v[86:87], v[66:67], v[14:15] op_sel:[0,1,0]
	v_pk_fma_f32 v[16:17], v[88:89], v[66:67], v[16:17] op_sel:[0,1,0]
	v_pk_fma_f32 v[10:11], v[86:87], v[62:63], v[10:11] op_sel:[0,1,0]
	v_pk_fma_f32 v[12:13], v[88:89], v[62:63], v[12:13] op_sel:[0,1,0]
	v_pk_fma_f32 v[6:7], v[86:87], v[70:71], v[6:7] op_sel:[0,1,0]
	v_pk_fma_f32 v[8:9], v[88:89], v[70:71], v[8:9] op_sel:[0,1,0]
	v_pk_fma_f32 v[2:3], v[86:87], v[50:51], v[2:3] op_sel:[0,1,0]
	v_pk_fma_f32 v[4:5], v[88:89], v[50:51], v[4:5] op_sel:[0,1,0]
	s_waitcnt vmcnt(13)
	v_pk_fma_f32 v[36:37], v[92:93], v[48:49], v[36:37] op_sel_hi:[1,0,1]
	v_pk_fma_f32 v[34:35], v[90:91], v[48:49], v[34:35] op_sel_hi:[1,0,1]
	v_pk_fma_f32 v[32:33], v[92:93], v[40:41], v[32:33] op_sel_hi:[1,0,1]
	v_pk_fma_f32 v[30:31], v[90:91], v[40:41], v[30:31] op_sel_hi:[1,0,1]
	v_pk_fma_f32 v[28:29], v[92:93], v[44:45], v[28:29] op_sel_hi:[1,0,1]
	v_pk_fma_f32 v[26:27], v[90:91], v[44:45], v[26:27] op_sel_hi:[1,0,1]
	v_pk_fma_f32 v[24:25], v[92:93], v[60:61], v[24:25] op_sel_hi:[1,0,1]
	v_pk_fma_f32 v[22:23], v[90:91], v[60:61], v[22:23] op_sel_hi:[1,0,1]
	v_pk_fma_f32 v[20:21], v[92:93], v[56:57], v[20:21] op_sel_hi:[1,0,1]
	v_pk_fma_f32 v[18:19], v[90:91], v[56:57], v[18:19] op_sel_hi:[1,0,1]
	v_pk_fma_f32 v[16:17], v[92:93], v[68:69], v[16:17] op_sel_hi:[1,0,1]
	v_pk_fma_f32 v[14:15], v[90:91], v[68:69], v[14:15] op_sel_hi:[1,0,1]
	v_pk_fma_f32 v[12:13], v[92:93], v[64:65], v[12:13] op_sel_hi:[1,0,1]
	v_pk_fma_f32 v[10:11], v[90:91], v[64:65], v[10:11] op_sel_hi:[1,0,1]
	v_pk_fma_f32 v[8:9], v[92:93], v[72:73], v[8:9] op_sel_hi:[1,0,1]
	v_pk_fma_f32 v[6:7], v[90:91], v[72:73], v[6:7] op_sel_hi:[1,0,1]
	v_pk_fma_f32 v[4:5], v[92:93], v[52:53], v[4:5] op_sel_hi:[1,0,1]
	v_pk_fma_f32 v[2:3], v[90:91], v[52:53], v[2:3] op_sel_hi:[1,0,1]
	s_waitcnt vmcnt(12)
	v_pk_fma_f32 v[36:37], v[96:97], v[76:77], v[36:37] op_sel_hi:[1,0,1]
	v_pk_fma_f32 v[34:35], v[94:95], v[76:77], v[34:35] op_sel_hi:[1,0,1]
	v_pk_fma_f32 v[32:33], v[96:97], v[98:99], v[32:33] op_sel_hi:[1,0,1]
	v_pk_fma_f32 v[30:31], v[94:95], v[98:99], v[30:31] op_sel_hi:[1,0,1]
	v_pk_fma_f32 v[28:29], v[96:97], v[100:101], v[28:29] op_sel_hi:[1,0,1]
	v_pk_fma_f32 v[26:27], v[94:95], v[100:101], v[26:27] op_sel_hi:[1,0,1]
	v_pk_fma_f32 v[24:25], v[96:97], v[102:103], v[24:25] op_sel_hi:[1,0,1]
	v_pk_fma_f32 v[22:23], v[94:95], v[102:103], v[22:23] op_sel_hi:[1,0,1]
	v_pk_fma_f32 v[20:21], v[96:97], v[104:105], v[20:21] op_sel_hi:[1,0,1]
	v_pk_fma_f32 v[18:19], v[94:95], v[104:105], v[18:19] op_sel_hi:[1,0,1]
	v_pk_fma_f32 v[16:17], v[96:97], v[106:107], v[16:17] op_sel_hi:[1,0,1]
	v_pk_fma_f32 v[14:15], v[94:95], v[106:107], v[14:15] op_sel_hi:[1,0,1]
	v_pk_fma_f32 v[12:13], v[96:97], v[108:109], v[12:13] op_sel_hi:[1,0,1]
	v_pk_fma_f32 v[10:11], v[94:95], v[108:109], v[10:11] op_sel_hi:[1,0,1]
	v_pk_fma_f32 v[8:9], v[96:97], v[110:111], v[8:9] op_sel_hi:[1,0,1]
	v_pk_fma_f32 v[6:7], v[94:95], v[110:111], v[6:7] op_sel_hi:[1,0,1]
	v_pk_fma_f32 v[4:5], v[96:97], v[112:113], v[4:5] op_sel_hi:[1,0,1]
	v_pk_fma_f32 v[2:3], v[94:95], v[112:113], v[2:3] op_sel_hi:[1,0,1]
	v_lshl_add_u64 v[196:197], v[74:75], 0, s[6:7]
	global_load_dwordx4 v[82:85], v[196:197], off
	v_lshl_add_u64 v[198:199], v[196:197], 0, v[200:201]
	global_load_dwordx4 v[86:89], v[198:199], off
	v_lshl_add_u64 v[198:199], v[196:197], 0, v[202:203]
	global_load_dwordx4 v[90:93], v[198:199], off
	v_lshl_add_u64 v[198:199], v[196:197], 0, v[204:205]
	global_load_dwordx4 v[94:97], v[198:199], off
	s_add_u32 s6, s6, 0x18000
	s_addc_u32 s7, s7, 0
	ds_read_b128 v[38:41], v80 offset:4096
	ds_read_b128 v[42:45], v80 offset:8192
	ds_read_b128 v[46:49], v80
	ds_read_b128 v[50:53], v80 offset:32768
	ds_read_b128 v[58:61], v80 offset:12288
	ds_read_b128 v[54:57], v80 offset:16384
	ds_read_b128 v[66:69], v80 offset:20480
	ds_read_b128 v[62:65], v80 offset:24576
	ds_read_b128 v[70:73], v80 offset:28672
	s_waitcnt lgkmcnt(6)
	v_mov_b32_e32 v76, v49
	v_mov_b32_e32 v98, v41
	v_mov_b32_e32 v100, v45
	s_waitcnt lgkmcnt(4)
	v_mov_b32_e32 v102, v61
	s_waitcnt lgkmcnt(3)
	v_mov_b32_e32 v104, v57
	s_waitcnt lgkmcnt(2)
	v_mov_b32_e32 v106, v69
	s_waitcnt lgkmcnt(1)
	v_mov_b32_e32 v108, v65
	s_waitcnt lgkmcnt(0)
	v_mov_b32_e32 v110, v73
	v_mov_b32_e32 v112, v53
	v_add_u32_e32 v80, 16, v80
	s_waitcnt vmcnt(15)
	v_pk_fma_f32 v[36:37], v[150:151], v[46:47], v[36:37] op_sel_hi:[1,0,1]
	v_pk_fma_f32 v[34:35], v[148:149], v[46:47], v[34:35] op_sel_hi:[1,0,1]
	v_pk_fma_f32 v[32:33], v[150:151], v[38:39], v[32:33] op_sel_hi:[1,0,1]
	v_pk_fma_f32 v[30:31], v[148:149], v[38:39], v[30:31] op_sel_hi:[1,0,1]
	v_pk_fma_f32 v[28:29], v[150:151], v[42:43], v[28:29] op_sel_hi:[1,0,1]
	v_pk_fma_f32 v[26:27], v[148:149], v[42:43], v[26:27] op_sel_hi:[1,0,1]
	v_pk_fma_f32 v[24:25], v[150:151], v[58:59], v[24:25] op_sel_hi:[1,0,1]
	v_pk_fma_f32 v[22:23], v[148:149], v[58:59], v[22:23] op_sel_hi:[1,0,1]
	v_pk_fma_f32 v[20:21], v[150:151], v[54:55], v[20:21] op_sel_hi:[1,0,1]
	v_pk_fma_f32 v[18:19], v[148:149], v[54:55], v[18:19] op_sel_hi:[1,0,1]
	v_pk_fma_f32 v[16:17], v[150:151], v[66:67], v[16:17] op_sel_hi:[1,0,1]
	v_pk_fma_f32 v[14:15], v[148:149], v[66:67], v[14:15] op_sel_hi:[1,0,1]
	v_pk_fma_f32 v[12:13], v[150:151], v[62:63], v[12:13] op_sel_hi:[1,0,1]
	v_pk_fma_f32 v[10:11], v[148:149], v[62:63], v[10:11] op_sel_hi:[1,0,1]
	v_pk_fma_f32 v[8:9], v[150:151], v[70:71], v[8:9] op_sel_hi:[1,0,1]
	v_pk_fma_f32 v[6:7], v[148:149], v[70:71], v[6:7] op_sel_hi:[1,0,1]
	v_pk_fma_f32 v[4:5], v[150:151], v[50:51], v[4:5] op_sel_hi:[1,0,1]
	v_pk_fma_f32 v[2:3], v[148:149], v[50:51], v[2:3] op_sel_hi:[1,0,1]
	s_waitcnt vmcnt(14)
	v_pk_fma_f32 v[34:35], v[152:153], v[46:47], v[34:35] op_sel:[0,1,0]
	v_pk_fma_f32 v[36:37], v[154:155], v[46:47], v[36:37] op_sel:[0,1,0]
	v_pk_fma_f32 v[30:31], v[152:153], v[38:39], v[30:31] op_sel:[0,1,0]
	v_pk_fma_f32 v[32:33], v[154:155], v[38:39], v[32:33] op_sel:[0,1,0]
	v_pk_fma_f32 v[26:27], v[152:153], v[42:43], v[26:27] op_sel:[0,1,0]
	v_pk_fma_f32 v[28:29], v[154:155], v[42:43], v[28:29] op_sel:[0,1,0]
	v_pk_fma_f32 v[22:23], v[152:153], v[58:59], v[22:23] op_sel:[0,1,0]
	v_pk_fma_f32 v[24:25], v[154:155], v[58:59], v[24:25] op_sel:[0,1,0]
	v_pk_fma_f32 v[18:19], v[152:153], v[54:55], v[18:19] op_sel:[0,1,0]
	v_pk_fma_f32 v[20:21], v[154:155], v[54:55], v[20:21] op_sel:[0,1,0]
	v_pk_fma_f32 v[14:15], v[152:153], v[66:67], v[14:15] op_sel:[0,1,0]
	v_pk_fma_f32 v[16:17], v[154:155], v[66:67], v[16:17] op_sel:[0,1,0]
	v_pk_fma_f32 v[10:11], v[152:153], v[62:63], v[10:11] op_sel:[0,1,0]
	v_pk_fma_f32 v[12:13], v[154:155], v[62:63], v[12:13] op_sel:[0,1,0]
	v_pk_fma_f32 v[6:7], v[152:153], v[70:71], v[6:7] op_sel:[0,1,0]
	v_pk_fma_f32 v[8:9], v[154:155], v[70:71], v[8:9] op_sel:[0,1,0]
	v_pk_fma_f32 v[2:3], v[152:153], v[50:51], v[2:3] op_sel:[0,1,0]
	v_pk_fma_f32 v[4:5], v[154:155], v[50:51], v[4:5] op_sel:[0,1,0]
	s_waitcnt vmcnt(13)
	v_pk_fma_f32 v[36:37], v[158:159], v[48:49], v[36:37] op_sel_hi:[1,0,1]
	v_pk_fma_f32 v[34:35], v[156:157], v[48:49], v[34:35] op_sel_hi:[1,0,1]
	v_pk_fma_f32 v[32:33], v[158:159], v[40:41], v[32:33] op_sel_hi:[1,0,1]
	v_pk_fma_f32 v[30:31], v[156:157], v[40:41], v[30:31] op_sel_hi:[1,0,1]
	v_pk_fma_f32 v[28:29], v[158:159], v[44:45], v[28:29] op_sel_hi:[1,0,1]
	v_pk_fma_f32 v[26:27], v[156:157], v[44:45], v[26:27] op_sel_hi:[1,0,1]
	v_pk_fma_f32 v[24:25], v[158:159], v[60:61], v[24:25] op_sel_hi:[1,0,1]
	v_pk_fma_f32 v[22:23], v[156:157], v[60:61], v[22:23] op_sel_hi:[1,0,1]
	v_pk_fma_f32 v[20:21], v[158:159], v[56:57], v[20:21] op_sel_hi:[1,0,1]
	v_pk_fma_f32 v[18:19], v[156:157], v[56:57], v[18:19] op_sel_hi:[1,0,1]
	v_pk_fma_f32 v[16:17], v[158:159], v[68:69], v[16:17] op_sel_hi:[1,0,1]
	v_pk_fma_f32 v[14:15], v[156:157], v[68:69], v[14:15] op_sel_hi:[1,0,1]
	v_pk_fma_f32 v[12:13], v[158:159], v[64:65], v[12:13] op_sel_hi:[1,0,1]
	v_pk_fma_f32 v[10:11], v[156:157], v[64:65], v[10:11] op_sel_hi:[1,0,1]
	v_pk_fma_f32 v[8:9], v[158:159], v[72:73], v[8:9] op_sel_hi:[1,0,1]
	v_pk_fma_f32 v[6:7], v[156:157], v[72:73], v[6:7] op_sel_hi:[1,0,1]
	v_pk_fma_f32 v[4:5], v[158:159], v[52:53], v[4:5] op_sel_hi:[1,0,1]
	v_pk_fma_f32 v[2:3], v[156:157], v[52:53], v[2:3] op_sel_hi:[1,0,1]
	s_waitcnt vmcnt(12)
	v_pk_fma_f32 v[36:37], v[162:163], v[76:77], v[36:37] op_sel_hi:[1,0,1]
	v_pk_fma_f32 v[34:35], v[160:161], v[76:77], v[34:35] op_sel_hi:[1,0,1]
	v_pk_fma_f32 v[32:33], v[162:163], v[98:99], v[32:33] op_sel_hi:[1,0,1]
	v_pk_fma_f32 v[30:31], v[160:161], v[98:99], v[30:31] op_sel_hi:[1,0,1]
	v_pk_fma_f32 v[28:29], v[162:163], v[100:101], v[28:29] op_sel_hi:[1,0,1]
	v_pk_fma_f32 v[26:27], v[160:161], v[100:101], v[26:27] op_sel_hi:[1,0,1]
	v_pk_fma_f32 v[24:25], v[162:163], v[102:103], v[24:25] op_sel_hi:[1,0,1]
	v_pk_fma_f32 v[22:23], v[160:161], v[102:103], v[22:23] op_sel_hi:[1,0,1]
	v_pk_fma_f32 v[20:21], v[162:163], v[104:105], v[20:21] op_sel_hi:[1,0,1]
	v_pk_fma_f32 v[18:19], v[160:161], v[104:105], v[18:19] op_sel_hi:[1,0,1]
	v_pk_fma_f32 v[16:17], v[162:163], v[106:107], v[16:17] op_sel_hi:[1,0,1]
	v_pk_fma_f32 v[14:15], v[160:161], v[106:107], v[14:15] op_sel_hi:[1,0,1]
	v_pk_fma_f32 v[12:13], v[162:163], v[108:109], v[12:13] op_sel_hi:[1,0,1]
	v_pk_fma_f32 v[10:11], v[160:161], v[108:109], v[10:11] op_sel_hi:[1,0,1]
	v_pk_fma_f32 v[8:9], v[162:163], v[110:111], v[8:9] op_sel_hi:[1,0,1]
	v_pk_fma_f32 v[6:7], v[160:161], v[110:111], v[6:7] op_sel_hi:[1,0,1]
	v_pk_fma_f32 v[4:5], v[162:163], v[112:113], v[4:5] op_sel_hi:[1,0,1]
	v_pk_fma_f32 v[2:3], v[160:161], v[112:113], v[2:3] op_sel_hi:[1,0,1]
	v_lshl_add_u64 v[196:197], v[74:75], 0, s[6:7]
	global_load_dwordx4 v[148:151], v[196:197], off
	v_lshl_add_u64 v[198:199], v[196:197], 0, v[200:201]
	global_load_dwordx4 v[152:155], v[198:199], off
	v_lshl_add_u64 v[198:199], v[196:197], 0, v[202:203]
	global_load_dwordx4 v[156:159], v[198:199], off
	v_lshl_add_u64 v[198:199], v[196:197], 0, v[204:205]
	global_load_dwordx4 v[160:163], v[198:199], off
	s_add_u32 s6, s6, 0x18000
	s_addc_u32 s7, s7, 0
	ds_read_b128 v[38:41], v80 offset:4096
	ds_read_b128 v[42:45], v80 offset:8192
	ds_read_b128 v[46:49], v80
	ds_read_b128 v[50:53], v80 offset:32768
	ds_read_b128 v[58:61], v80 offset:12288
	ds_read_b128 v[54:57], v80 offset:16384
	ds_read_b128 v[66:69], v80 offset:20480
	ds_read_b128 v[62:65], v80 offset:24576
	ds_read_b128 v[70:73], v80 offset:28672
	s_waitcnt lgkmcnt(6)
	v_mov_b32_e32 v76, v49
	v_mov_b32_e32 v98, v41
	v_mov_b32_e32 v100, v45
	s_waitcnt lgkmcnt(4)
	v_mov_b32_e32 v102, v61
	s_waitcnt lgkmcnt(3)
	v_mov_b32_e32 v104, v57
	s_waitcnt lgkmcnt(2)
	v_mov_b32_e32 v106, v69
	s_waitcnt lgkmcnt(1)
	v_mov_b32_e32 v108, v65
	s_waitcnt lgkmcnt(0)
	v_mov_b32_e32 v110, v73
	v_mov_b32_e32 v112, v53
	v_add_u32_e32 v80, 16, v80
	s_waitcnt vmcnt(15)
	v_pk_fma_f32 v[36:37], v[166:167], v[46:47], v[36:37] op_sel_hi:[1,0,1]
	v_pk_fma_f32 v[34:35], v[164:165], v[46:47], v[34:35] op_sel_hi:[1,0,1]
	v_pk_fma_f32 v[32:33], v[166:167], v[38:39], v[32:33] op_sel_hi:[1,0,1]
	v_pk_fma_f32 v[30:31], v[164:165], v[38:39], v[30:31] op_sel_hi:[1,0,1]
	v_pk_fma_f32 v[28:29], v[166:167], v[42:43], v[28:29] op_sel_hi:[1,0,1]
	v_pk_fma_f32 v[26:27], v[164:165], v[42:43], v[26:27] op_sel_hi:[1,0,1]
	v_pk_fma_f32 v[24:25], v[166:167], v[58:59], v[24:25] op_sel_hi:[1,0,1]
	v_pk_fma_f32 v[22:23], v[164:165], v[58:59], v[22:23] op_sel_hi:[1,0,1]
	v_pk_fma_f32 v[20:21], v[166:167], v[54:55], v[20:21] op_sel_hi:[1,0,1]
	v_pk_fma_f32 v[18:19], v[164:165], v[54:55], v[18:19] op_sel_hi:[1,0,1]
	v_pk_fma_f32 v[16:17], v[166:167], v[66:67], v[16:17] op_sel_hi:[1,0,1]
	v_pk_fma_f32 v[14:15], v[164:165], v[66:67], v[14:15] op_sel_hi:[1,0,1]
	v_pk_fma_f32 v[12:13], v[166:167], v[62:63], v[12:13] op_sel_hi:[1,0,1]
	v_pk_fma_f32 v[10:11], v[164:165], v[62:63], v[10:11] op_sel_hi:[1,0,1]
	v_pk_fma_f32 v[8:9], v[166:167], v[70:71], v[8:9] op_sel_hi:[1,0,1]
	v_pk_fma_f32 v[6:7], v[164:165], v[70:71], v[6:7] op_sel_hi:[1,0,1]
	v_pk_fma_f32 v[4:5], v[166:167], v[50:51], v[4:5] op_sel_hi:[1,0,1]
	v_pk_fma_f32 v[2:3], v[164:165], v[50:51], v[2:3] op_sel_hi:[1,0,1]
	s_waitcnt vmcnt(14)
	v_pk_fma_f32 v[34:35], v[168:169], v[46:47], v[34:35] op_sel:[0,1,0]
	v_pk_fma_f32 v[36:37], v[170:171], v[46:47], v[36:37] op_sel:[0,1,0]
	v_pk_fma_f32 v[30:31], v[168:169], v[38:39], v[30:31] op_sel:[0,1,0]
	v_pk_fma_f32 v[32:33], v[170:171], v[38:39], v[32:33] op_sel:[0,1,0]
	v_pk_fma_f32 v[26:27], v[168:169], v[42:43], v[26:27] op_sel:[0,1,0]
	v_pk_fma_f32 v[28:29], v[170:171], v[42:43], v[28:29] op_sel:[0,1,0]
	v_pk_fma_f32 v[22:23], v[168:169], v[58:59], v[22:23] op_sel:[0,1,0]
	v_pk_fma_f32 v[24:25], v[170:171], v[58:59], v[24:25] op_sel:[0,1,0]
	v_pk_fma_f32 v[18:19], v[168:169], v[54:55], v[18:19] op_sel:[0,1,0]
	v_pk_fma_f32 v[20:21], v[170:171], v[54:55], v[20:21] op_sel:[0,1,0]
	v_pk_fma_f32 v[14:15], v[168:169], v[66:67], v[14:15] op_sel:[0,1,0]
	v_pk_fma_f32 v[16:17], v[170:171], v[66:67], v[16:17] op_sel:[0,1,0]
	v_pk_fma_f32 v[10:11], v[168:169], v[62:63], v[10:11] op_sel:[0,1,0]
	v_pk_fma_f32 v[12:13], v[170:171], v[62:63], v[12:13] op_sel:[0,1,0]
	v_pk_fma_f32 v[6:7], v[168:169], v[70:71], v[6:7] op_sel:[0,1,0]
	v_pk_fma_f32 v[8:9], v[170:171], v[70:71], v[8:9] op_sel:[0,1,0]
	v_pk_fma_f32 v[2:3], v[168:169], v[50:51], v[2:3] op_sel:[0,1,0]
	v_pk_fma_f32 v[4:5], v[170:171], v[50:51], v[4:5] op_sel:[0,1,0]
	s_waitcnt vmcnt(13)
	v_pk_fma_f32 v[36:37], v[174:175], v[48:49], v[36:37] op_sel_hi:[1,0,1]
	v_pk_fma_f32 v[34:35], v[172:173], v[48:49], v[34:35] op_sel_hi:[1,0,1]
	v_pk_fma_f32 v[32:33], v[174:175], v[40:41], v[32:33] op_sel_hi:[1,0,1]
	v_pk_fma_f32 v[30:31], v[172:173], v[40:41], v[30:31] op_sel_hi:[1,0,1]
	v_pk_fma_f32 v[28:29], v[174:175], v[44:45], v[28:29] op_sel_hi:[1,0,1]
	v_pk_fma_f32 v[26:27], v[172:173], v[44:45], v[26:27] op_sel_hi:[1,0,1]
	v_pk_fma_f32 v[24:25], v[174:175], v[60:61], v[24:25] op_sel_hi:[1,0,1]
	v_pk_fma_f32 v[22:23], v[172:173], v[60:61], v[22:23] op_sel_hi:[1,0,1]
	v_pk_fma_f32 v[20:21], v[174:175], v[56:57], v[20:21] op_sel_hi:[1,0,1]
	v_pk_fma_f32 v[18:19], v[172:173], v[56:57], v[18:19] op_sel_hi:[1,0,1]
	v_pk_fma_f32 v[16:17], v[174:175], v[68:69], v[16:17] op_sel_hi:[1,0,1]
	v_pk_fma_f32 v[14:15], v[172:173], v[68:69], v[14:15] op_sel_hi:[1,0,1]
	v_pk_fma_f32 v[12:13], v[174:175], v[64:65], v[12:13] op_sel_hi:[1,0,1]
	v_pk_fma_f32 v[10:11], v[172:173], v[64:65], v[10:11] op_sel_hi:[1,0,1]
	v_pk_fma_f32 v[8:9], v[174:175], v[72:73], v[8:9] op_sel_hi:[1,0,1]
	v_pk_fma_f32 v[6:7], v[172:173], v[72:73], v[6:7] op_sel_hi:[1,0,1]
	v_pk_fma_f32 v[4:5], v[174:175], v[52:53], v[4:5] op_sel_hi:[1,0,1]
	v_pk_fma_f32 v[2:3], v[172:173], v[52:53], v[2:3] op_sel_hi:[1,0,1]
	s_waitcnt vmcnt(12)
	v_pk_fma_f32 v[36:37], v[178:179], v[76:77], v[36:37] op_sel_hi:[1,0,1]
	v_pk_fma_f32 v[34:35], v[176:177], v[76:77], v[34:35] op_sel_hi:[1,0,1]
	v_pk_fma_f32 v[32:33], v[178:179], v[98:99], v[32:33] op_sel_hi:[1,0,1]
	v_pk_fma_f32 v[30:31], v[176:177], v[98:99], v[30:31] op_sel_hi:[1,0,1]
	v_pk_fma_f32 v[28:29], v[178:179], v[100:101], v[28:29] op_sel_hi:[1,0,1]
	v_pk_fma_f32 v[26:27], v[176:177], v[100:101], v[26:27] op_sel_hi:[1,0,1]
	v_pk_fma_f32 v[24:25], v[178:179], v[102:103], v[24:25] op_sel_hi:[1,0,1]
	v_pk_fma_f32 v[22:23], v[176:177], v[102:103], v[22:23] op_sel_hi:[1,0,1]
	v_pk_fma_f32 v[20:21], v[178:179], v[104:105], v[20:21] op_sel_hi:[1,0,1]
	v_pk_fma_f32 v[18:19], v[176:177], v[104:105], v[18:19] op_sel_hi:[1,0,1]
	v_pk_fma_f32 v[16:17], v[178:179], v[106:107], v[16:17] op_sel_hi:[1,0,1]
	v_pk_fma_f32 v[14:15], v[176:177], v[106:107], v[14:15] op_sel_hi:[1,0,1]
	v_pk_fma_f32 v[12:13], v[178:179], v[108:109], v[12:13] op_sel_hi:[1,0,1]
	v_pk_fma_f32 v[10:11], v[176:177], v[108:109], v[10:11] op_sel_hi:[1,0,1]
	v_pk_fma_f32 v[8:9], v[178:179], v[110:111], v[8:9] op_sel_hi:[1,0,1]
	v_pk_fma_f32 v[6:7], v[176:177], v[110:111], v[6:7] op_sel_hi:[1,0,1]
	v_pk_fma_f32 v[4:5], v[178:179], v[112:113], v[4:5] op_sel_hi:[1,0,1]
	v_pk_fma_f32 v[2:3], v[176:177], v[112:113], v[2:3] op_sel_hi:[1,0,1]
	v_lshl_add_u64 v[196:197], v[74:75], 0, s[6:7]
	global_load_dwordx4 v[164:167], v[196:197], off
	v_lshl_add_u64 v[198:199], v[196:197], 0, v[200:201]
	global_load_dwordx4 v[168:171], v[198:199], off
	v_lshl_add_u64 v[198:199], v[196:197], 0, v[202:203]
	global_load_dwordx4 v[172:175], v[198:199], off
	v_lshl_add_u64 v[198:199], v[196:197], 0, v[204:205]
	global_load_dwordx4 v[176:179], v[198:199], off
	s_add_u32 s6, s6, 0x18000
	s_addc_u32 s7, s7, 0
	ds_read_b128 v[38:41], v80 offset:4096
	ds_read_b128 v[42:45], v80 offset:8192
	ds_read_b128 v[46:49], v80
	ds_read_b128 v[50:53], v80 offset:32768
	ds_read_b128 v[58:61], v80 offset:12288
	ds_read_b128 v[54:57], v80 offset:16384
	ds_read_b128 v[66:69], v80 offset:20480
	ds_read_b128 v[62:65], v80 offset:24576
	ds_read_b128 v[70:73], v80 offset:28672
	s_waitcnt lgkmcnt(6)
	v_mov_b32_e32 v76, v49
	v_mov_b32_e32 v98, v41
	v_mov_b32_e32 v100, v45
	s_waitcnt lgkmcnt(4)
	v_mov_b32_e32 v102, v61
	s_waitcnt lgkmcnt(3)
	v_mov_b32_e32 v104, v57
	s_waitcnt lgkmcnt(2)
	v_mov_b32_e32 v106, v69
	s_waitcnt lgkmcnt(1)
	v_mov_b32_e32 v108, v65
	s_waitcnt lgkmcnt(0)
	v_mov_b32_e32 v110, v73
	v_mov_b32_e32 v112, v53
	v_add_u32_e32 v80, 16, v80
	s_waitcnt vmcnt(15)
	v_pk_fma_f32 v[36:37], v[182:183], v[46:47], v[36:37] op_sel_hi:[1,0,1]
	v_pk_fma_f32 v[34:35], v[180:181], v[46:47], v[34:35] op_sel_hi:[1,0,1]
	v_pk_fma_f32 v[32:33], v[182:183], v[38:39], v[32:33] op_sel_hi:[1,0,1]
	v_pk_fma_f32 v[30:31], v[180:181], v[38:39], v[30:31] op_sel_hi:[1,0,1]
	v_pk_fma_f32 v[28:29], v[182:183], v[42:43], v[28:29] op_sel_hi:[1,0,1]
	v_pk_fma_f32 v[26:27], v[180:181], v[42:43], v[26:27] op_sel_hi:[1,0,1]
	v_pk_fma_f32 v[24:25], v[182:183], v[58:59], v[24:25] op_sel_hi:[1,0,1]
	v_pk_fma_f32 v[22:23], v[180:181], v[58:59], v[22:23] op_sel_hi:[1,0,1]
	v_pk_fma_f32 v[20:21], v[182:183], v[54:55], v[20:21] op_sel_hi:[1,0,1]
	v_pk_fma_f32 v[18:19], v[180:181], v[54:55], v[18:19] op_sel_hi:[1,0,1]
	v_pk_fma_f32 v[16:17], v[182:183], v[66:67], v[16:17] op_sel_hi:[1,0,1]
	v_pk_fma_f32 v[14:15], v[180:181], v[66:67], v[14:15] op_sel_hi:[1,0,1]
	v_pk_fma_f32 v[12:13], v[182:183], v[62:63], v[12:13] op_sel_hi:[1,0,1]
	v_pk_fma_f32 v[10:11], v[180:181], v[62:63], v[10:11] op_sel_hi:[1,0,1]
	v_pk_fma_f32 v[8:9], v[182:183], v[70:71], v[8:9] op_sel_hi:[1,0,1]
	v_pk_fma_f32 v[6:7], v[180:181], v[70:71], v[6:7] op_sel_hi:[1,0,1]
	v_pk_fma_f32 v[4:5], v[182:183], v[50:51], v[4:5] op_sel_hi:[1,0,1]
	v_pk_fma_f32 v[2:3], v[180:181], v[50:51], v[2:3] op_sel_hi:[1,0,1]
	s_waitcnt vmcnt(14)
	v_pk_fma_f32 v[34:35], v[184:185], v[46:47], v[34:35] op_sel:[0,1,0]
	v_pk_fma_f32 v[36:37], v[186:187], v[46:47], v[36:37] op_sel:[0,1,0]
	v_pk_fma_f32 v[30:31], v[184:185], v[38:39], v[30:31] op_sel:[0,1,0]
	v_pk_fma_f32 v[32:33], v[186:187], v[38:39], v[32:33] op_sel:[0,1,0]
	v_pk_fma_f32 v[26:27], v[184:185], v[42:43], v[26:27] op_sel:[0,1,0]
	v_pk_fma_f32 v[28:29], v[186:187], v[42:43], v[28:29] op_sel:[0,1,0]
	v_pk_fma_f32 v[22:23], v[184:185], v[58:59], v[22:23] op_sel:[0,1,0]
	v_pk_fma_f32 v[24:25], v[186:187], v[58:59], v[24:25] op_sel:[0,1,0]
	v_pk_fma_f32 v[18:19], v[184:185], v[54:55], v[18:19] op_sel:[0,1,0]
	v_pk_fma_f32 v[20:21], v[186:187], v[54:55], v[20:21] op_sel:[0,1,0]
	v_pk_fma_f32 v[14:15], v[184:185], v[66:67], v[14:15] op_sel:[0,1,0]
	v_pk_fma_f32 v[16:17], v[186:187], v[66:67], v[16:17] op_sel:[0,1,0]
	v_pk_fma_f32 v[10:11], v[184:185], v[62:63], v[10:11] op_sel:[0,1,0]
	v_pk_fma_f32 v[12:13], v[186:187], v[62:63], v[12:13] op_sel:[0,1,0]
	v_pk_fma_f32 v[6:7], v[184:185], v[70:71], v[6:7] op_sel:[0,1,0]
	v_pk_fma_f32 v[8:9], v[186:187], v[70:71], v[8:9] op_sel:[0,1,0]
	v_pk_fma_f32 v[2:3], v[184:185], v[50:51], v[2:3] op_sel:[0,1,0]
	v_pk_fma_f32 v[4:5], v[186:187], v[50:51], v[4:5] op_sel:[0,1,0]
	s_waitcnt vmcnt(13)
	v_pk_fma_f32 v[36:37], v[190:191], v[48:49], v[36:37] op_sel_hi:[1,0,1]
	v_pk_fma_f32 v[34:35], v[188:189], v[48:49], v[34:35] op_sel_hi:[1,0,1]
	v_pk_fma_f32 v[32:33], v[190:191], v[40:41], v[32:33] op_sel_hi:[1,0,1]
	v_pk_fma_f32 v[30:31], v[188:189], v[40:41], v[30:31] op_sel_hi:[1,0,1]
	v_pk_fma_f32 v[28:29], v[190:191], v[44:45], v[28:29] op_sel_hi:[1,0,1]
	v_pk_fma_f32 v[26:27], v[188:189], v[44:45], v[26:27] op_sel_hi:[1,0,1]
	v_pk_fma_f32 v[24:25], v[190:191], v[60:61], v[24:25] op_sel_hi:[1,0,1]
	v_pk_fma_f32 v[22:23], v[188:189], v[60:61], v[22:23] op_sel_hi:[1,0,1]
	v_pk_fma_f32 v[20:21], v[190:191], v[56:57], v[20:21] op_sel_hi:[1,0,1]
	v_pk_fma_f32 v[18:19], v[188:189], v[56:57], v[18:19] op_sel_hi:[1,0,1]
	v_pk_fma_f32 v[16:17], v[190:191], v[68:69], v[16:17] op_sel_hi:[1,0,1]
	v_pk_fma_f32 v[14:15], v[188:189], v[68:69], v[14:15] op_sel_hi:[1,0,1]
	v_pk_fma_f32 v[12:13], v[190:191], v[64:65], v[12:13] op_sel_hi:[1,0,1]
	v_pk_fma_f32 v[10:11], v[188:189], v[64:65], v[10:11] op_sel_hi:[1,0,1]
	v_pk_fma_f32 v[8:9], v[190:191], v[72:73], v[8:9] op_sel_hi:[1,0,1]
	v_pk_fma_f32 v[6:7], v[188:189], v[72:73], v[6:7] op_sel_hi:[1,0,1]
	v_pk_fma_f32 v[4:5], v[190:191], v[52:53], v[4:5] op_sel_hi:[1,0,1]
	v_pk_fma_f32 v[2:3], v[188:189], v[52:53], v[2:3] op_sel_hi:[1,0,1]
	s_waitcnt vmcnt(12)
	v_pk_fma_f32 v[36:37], v[194:195], v[76:77], v[36:37] op_sel_hi:[1,0,1]
	v_pk_fma_f32 v[34:35], v[192:193], v[76:77], v[34:35] op_sel_hi:[1,0,1]
	v_pk_fma_f32 v[32:33], v[194:195], v[98:99], v[32:33] op_sel_hi:[1,0,1]
	v_pk_fma_f32 v[30:31], v[192:193], v[98:99], v[30:31] op_sel_hi:[1,0,1]
	v_pk_fma_f32 v[28:29], v[194:195], v[100:101], v[28:29] op_sel_hi:[1,0,1]
	v_pk_fma_f32 v[26:27], v[192:193], v[100:101], v[26:27] op_sel_hi:[1,0,1]
	v_pk_fma_f32 v[24:25], v[194:195], v[102:103], v[24:25] op_sel_hi:[1,0,1]
	v_pk_fma_f32 v[22:23], v[192:193], v[102:103], v[22:23] op_sel_hi:[1,0,1]
	v_pk_fma_f32 v[20:21], v[194:195], v[104:105], v[20:21] op_sel_hi:[1,0,1]
	v_pk_fma_f32 v[18:19], v[192:193], v[104:105], v[18:19] op_sel_hi:[1,0,1]
	v_pk_fma_f32 v[16:17], v[194:195], v[106:107], v[16:17] op_sel_hi:[1,0,1]
	v_pk_fma_f32 v[14:15], v[192:193], v[106:107], v[14:15] op_sel_hi:[1,0,1]
	v_pk_fma_f32 v[12:13], v[194:195], v[108:109], v[12:13] op_sel_hi:[1,0,1]
	v_pk_fma_f32 v[10:11], v[192:193], v[108:109], v[10:11] op_sel_hi:[1,0,1]
	v_pk_fma_f32 v[8:9], v[194:195], v[110:111], v[8:9] op_sel_hi:[1,0,1]
	v_pk_fma_f32 v[6:7], v[192:193], v[110:111], v[6:7] op_sel_hi:[1,0,1]
	v_pk_fma_f32 v[4:5], v[194:195], v[112:113], v[4:5] op_sel_hi:[1,0,1]
	v_pk_fma_f32 v[2:3], v[192:193], v[112:113], v[2:3] op_sel_hi:[1,0,1]
	v_lshl_add_u64 v[196:197], v[74:75], 0, s[6:7]
	global_load_dwordx4 v[180:183], v[196:197], off
	v_lshl_add_u64 v[198:199], v[196:197], 0, v[200:201]
	global_load_dwordx4 v[184:187], v[198:199], off
	v_lshl_add_u64 v[198:199], v[196:197], 0, v[202:203]
	global_load_dwordx4 v[188:191], v[198:199], off
	v_lshl_add_u64 v[198:199], v[196:197], 0, v[204:205]
	global_load_dwordx4 v[192:195], v[198:199], off
	s_add_u32 s6, s6, 0x18000
	s_addc_u32 s7, s7, 0
	s_cmp_lg_u32 s6, 0x180000
	s_cbranch_scc1 .Ladaln_round
	ds_read_b128 v[38:41], v80 offset:4096
	ds_read_b128 v[42:45], v80 offset:8192
	ds_read_b128 v[46:49], v80
	ds_read_b128 v[50:53], v80 offset:32768
	ds_read_b128 v[58:61], v80 offset:12288
	ds_read_b128 v[54:57], v80 offset:16384
	ds_read_b128 v[66:69], v80 offset:20480
	ds_read_b128 v[62:65], v80 offset:24576
	ds_read_b128 v[70:73], v80 offset:28672
	s_waitcnt lgkmcnt(6)
	v_mov_b32_e32 v76, v49
	v_mov_b32_e32 v98, v41
	v_mov_b32_e32 v100, v45
	s_waitcnt lgkmcnt(4)
	v_mov_b32_e32 v102, v61
	s_waitcnt lgkmcnt(3)
	v_mov_b32_e32 v104, v57
	s_waitcnt lgkmcnt(2)
	v_mov_b32_e32 v106, v69
	s_waitcnt lgkmcnt(1)
	v_mov_b32_e32 v108, v65
	s_waitcnt lgkmcnt(0)
	v_mov_b32_e32 v110, v73
	v_mov_b32_e32 v112, v53
	v_add_u32_e32 v80, 16, v80
	s_waitcnt vmcnt(15)
	v_pk_fma_f32 v[36:37], v[84:85], v[46:47], v[36:37] op_sel_hi:[1,0,1]
	v_pk_fma_f32 v[34:35], v[82:83], v[46:47], v[34:35] op_sel_hi:[1,0,1]
	v_pk_fma_f32 v[32:33], v[84:85], v[38:39], v[32:33] op_sel_hi:[1,0,1]
	v_pk_fma_f32 v[30:31], v[82:83], v[38:39], v[30:31] op_sel_hi:[1,0,1]
	v_pk_fma_f32 v[28:29], v[84:85], v[42:43], v[28:29] op_sel_hi:[1,0,1]
	v_pk_fma_f32 v[26:27], v[82:83], v[42:43], v[26:27] op_sel_hi:[1,0,1]
	v_pk_fma_f32 v[24:25], v[84:85], v[58:59], v[24:25] op_sel_hi:[1,0,1]
	v_pk_fma_f32 v[22:23], v[82:83], v[58:59], v[22:23] op_sel_hi:[1,0,1]
	v_pk_fma_f32 v[20:21], v[84:85], v[54:55], v[20:21] op_sel_hi:[1,0,1]
	v_pk_fma_f32 v[18:19], v[82:83], v[54:55], v[18:19] op_sel_hi:[1,0,1]
	v_pk_fma_f32 v[16:17], v[84:85], v[66:67], v[16:17] op_sel_hi:[1,0,1]
	v_pk_fma_f32 v[14:15], v[82:83], v[66:67], v[14:15] op_sel_hi:[1,0,1]
	v_pk_fma_f32 v[12:13], v[84:85], v[62:63], v[12:13] op_sel_hi:[1,0,1]
	v_pk_fma_f32 v[10:11], v[82:83], v[62:63], v[10:11] op_sel_hi:[1,0,1]
	v_pk_fma_f32 v[8:9], v[84:85], v[70:71], v[8:9] op_sel_hi:[1,0,1]
	v_pk_fma_f32 v[6:7], v[82:83], v[70:71], v[6:7] op_sel_hi:[1,0,1]
	v_pk_fma_f32 v[4:5], v[84:85], v[50:51], v[4:5] op_sel_hi:[1,0,1]
	v_pk_fma_f32 v[2:3], v[82:83], v[50:51], v[2:3] op_sel_hi:[1,0,1]
	s_waitcnt vmcnt(14)
	v_pk_fma_f32 v[34:35], v[86:87], v[46:47], v[34:35] op_sel:[0,1,0]
	v_pk_fma_f32 v[36:37], v[88:89], v[46:47], v[36:37] op_sel:[0,1,0]
	v_pk_fma_f32 v[30:31], v[86:87], v[38:39], v[30:31] op_sel:[0,1,0]
	v_pk_fma_f32 v[32:33], v[88:89], v[38:39], v[32:33] op_sel:[0,1,0]
	v_pk_fma_f32 v[26:27], v[86:87], v[42:43], v[26:27] op_sel:[0,1,0]
	v_pk_fma_f32 v[28:29], v[88:89], v[42:43], v[28:29] op_sel:[0,1,0]
	v_pk_fma_f32 v[22:23], v[86:87], v[58:59], v[22:23] op_sel:[0,1,0]
	v_pk_fma_f32 v[24:25], v[88:89], v[58:59], v[24:25] op_sel:[0,1,0]
	v_pk_fma_f32 v[18:19], v[86:87], v[54:55], v[18:19] op_sel:[0,1,0]
	v_pk_fma_f32 v[20:21], v[88:89], v[54:55], v[20:21] op_sel:[0,1,0]
	v_pk_fma_f32 v[14:15], v[86:87], v[66:67], v[14:15] op_sel:[0,1,0]
	v_pk_fma_f32 v[16:17], v[88:89], v[66:67], v[16:17] op_sel:[0,1,0]
	v_pk_fma_f32 v[10:11], v[86:87], v[62:63], v[10:11] op_sel:[0,1,0]
	v_pk_fma_f32 v[12:13], v[88:89], v[62:63], v[12:13] op_sel:[0,1,0]
	v_pk_fma_f32 v[6:7], v[86:87], v[70:71], v[6:7] op_sel:[0,1,0]
	v_pk_fma_f32 v[8:9], v[88:89], v[70:71], v[8:9] op_sel:[0,1,0]
	v_pk_fma_f32 v[2:3], v[86:87], v[50:51], v[2:3] op_sel:[0,1,0]
	v_pk_fma_f32 v[4:5], v[88:89], v[50:51], v[4:5] op_sel:[0,1,0]
	s_waitcnt vmcnt(13)
	v_pk_fma_f32 v[36:37], v[92:93], v[48:49], v[36:37] op_sel_hi:[1,0,1]
	v_pk_fma_f32 v[34:35], v[90:91], v[48:49], v[34:35] op_sel_hi:[1,0,1]
	v_pk_fma_f32 v[32:33], v[92:93], v[40:41], v[32:33] op_sel_hi:[1,0,1]
	v_pk_fma_f32 v[30:31], v[90:91], v[40:41], v[30:31] op_sel_hi:[1,0,1]
	v_pk_fma_f32 v[28:29], v[92:93], v[44:45], v[28:29] op_sel_hi:[1,0,1]
	v_pk_fma_f32 v[26:27], v[90:91], v[44:45], v[26:27] op_sel_hi:[1,0,1]
	v_pk_fma_f32 v[24:25], v[92:93], v[60:61], v[24:25] op_sel_hi:[1,0,1]
	v_pk_fma_f32 v[22:23], v[90:91], v[60:61], v[22:23] op_sel_hi:[1,0,1]
	v_pk_fma_f32 v[20:21], v[92:93], v[56:57], v[20:21] op_sel_hi:[1,0,1]
	v_pk_fma_f32 v[18:19], v[90:91], v[56:57], v[18:19] op_sel_hi:[1,0,1]
	v_pk_fma_f32 v[16:17], v[92:93], v[68:69], v[16:17] op_sel_hi:[1,0,1]
	v_pk_fma_f32 v[14:15], v[90:91], v[68:69], v[14:15] op_sel_hi:[1,0,1]
	v_pk_fma_f32 v[12:13], v[92:93], v[64:65], v[12:13] op_sel_hi:[1,0,1]
	v_pk_fma_f32 v[10:11], v[90:91], v[64:65], v[10:11] op_sel_hi:[1,0,1]
	v_pk_fma_f32 v[8:9], v[92:93], v[72:73], v[8:9] op_sel_hi:[1,0,1]
	v_pk_fma_f32 v[6:7], v[90:91], v[72:73], v[6:7] op_sel_hi:[1,0,1]
	v_pk_fma_f32 v[4:5], v[92:93], v[52:53], v[4:5] op_sel_hi:[1,0,1]
	v_pk_fma_f32 v[2:3], v[90:91], v[52:53], v[2:3] op_sel_hi:[1,0,1]
	s_waitcnt vmcnt(12)
	v_pk_fma_f32 v[36:37], v[96:97], v[76:77], v[36:37] op_sel_hi:[1,0,1]
	v_pk_fma_f32 v[34:35], v[94:95], v[76:77], v[34:35] op_sel_hi:[1,0,1]
	v_pk_fma_f32 v[32:33], v[96:97], v[98:99], v[32:33] op_sel_hi:[1,0,1]
	v_pk_fma_f32 v[30:31], v[94:95], v[98:99], v[30:31] op_sel_hi:[1,0,1]
	v_pk_fma_f32 v[28:29], v[96:97], v[100:101], v[28:29] op_sel_hi:[1,0,1]
	v_pk_fma_f32 v[26:27], v[94:95], v[100:101], v[26:27] op_sel_hi:[1,0,1]
	v_pk_fma_f32 v[24:25], v[96:97], v[102:103], v[24:25] op_sel_hi:[1,0,1]
	v_pk_fma_f32 v[22:23], v[94:95], v[102:103], v[22:23] op_sel_hi:[1,0,1]
	v_pk_fma_f32 v[20:21], v[96:97], v[104:105], v[20:21] op_sel_hi:[1,0,1]
	v_pk_fma_f32 v[18:19], v[94:95], v[104:105], v[18:19] op_sel_hi:[1,0,1]
	v_pk_fma_f32 v[16:17], v[96:97], v[106:107], v[16:17] op_sel_hi:[1,0,1]
	v_pk_fma_f32 v[14:15], v[94:95], v[106:107], v[14:15] op_sel_hi:[1,0,1]
	v_pk_fma_f32 v[12:13], v[96:97], v[108:109], v[12:13] op_sel_hi:[1,0,1]
	v_pk_fma_f32 v[10:11], v[94:95], v[108:109], v[10:11] op_sel_hi:[1,0,1]
	v_pk_fma_f32 v[8:9], v[96:97], v[110:111], v[8:9] op_sel_hi:[1,0,1]
	v_pk_fma_f32 v[6:7], v[94:95], v[110:111], v[6:7] op_sel_hi:[1,0,1]
	v_pk_fma_f32 v[4:5], v[96:97], v[112:113], v[4:5] op_sel_hi:[1,0,1]
	v_pk_fma_f32 v[2:3], v[94:95], v[112:113], v[2:3] op_sel_hi:[1,0,1]
	ds_read_b128 v[38:41], v80 offset:4096
	ds_read_b128 v[42:45], v80 offset:8192
	ds_read_b128 v[46:49], v80
	ds_read_b128 v[50:53], v80 offset:32768
	ds_read_b128 v[58:61], v80 offset:12288
	ds_read_b128 v[54:57], v80 offset:16384
	ds_read_b128 v[66:69], v80 offset:20480
	ds_read_b128 v[62:65], v80 offset:24576
	ds_read_b128 v[70:73], v80 offset:28672
	s_waitcnt lgkmcnt(6)
	v_mov_b32_e32 v76, v49
	v_mov_b32_e32 v98, v41
	v_mov_b32_e32 v100, v45
	s_waitcnt lgkmcnt(4)
	v_mov_b32_e32 v102, v61
	s_waitcnt lgkmcnt(3)
	v_mov_b32_e32 v104, v57
	s_waitcnt lgkmcnt(2)
	v_mov_b32_e32 v106, v69
	s_waitcnt lgkmcnt(1)
	v_mov_b32_e32 v108, v65
	s_waitcnt lgkmcnt(0)
	v_mov_b32_e32 v110, v73
	v_mov_b32_e32 v112, v53
	v_add_u32_e32 v80, 16, v80
	s_waitcnt vmcnt(11)
	v_pk_fma_f32 v[36:37], v[150:151], v[46:47], v[36:37] op_sel_hi:[1,0,1]
	v_pk_fma_f32 v[34:35], v[148:149], v[46:47], v[34:35] op_sel_hi:[1,0,1]
	v_pk_fma_f32 v[32:33], v[150:151], v[38:39], v[32:33] op_sel_hi:[1,0,1]
	v_pk_fma_f32 v[30:31], v[148:149], v[38:39], v[30:31] op_sel_hi:[1,0,1]
	v_pk_fma_f32 v[28:29], v[150:151], v[42:43], v[28:29] op_sel_hi:[1,0,1]
	v_pk_fma_f32 v[26:27], v[148:149], v[42:43], v[26:27] op_sel_hi:[1,0,1]
	v_pk_fma_f32 v[24:25], v[150:151], v[58:59], v[24:25] op_sel_hi:[1,0,1]
	v_pk_fma_f32 v[22:23], v[148:149], v[58:59], v[22:23] op_sel_hi:[1,0,1]
	v_pk_fma_f32 v[20:21], v[150:151], v[54:55], v[20:21] op_sel_hi:[1,0,1]
	v_pk_fma_f32 v[18:19], v[148:149], v[54:55], v[18:19] op_sel_hi:[1,0,1]
	v_pk_fma_f32 v[16:17], v[150:151], v[66:67], v[16:17] op_sel_hi:[1,0,1]
	v_pk_fma_f32 v[14:15], v[148:149], v[66:67], v[14:15] op_sel_hi:[1,0,1]
	v_pk_fma_f32 v[12:13], v[150:151], v[62:63], v[12:13] op_sel_hi:[1,0,1]
	v_pk_fma_f32 v[10:11], v[148:149], v[62:63], v[10:11] op_sel_hi:[1,0,1]
	v_pk_fma_f32 v[8:9], v[150:151], v[70:71], v[8:9] op_sel_hi:[1,0,1]
	v_pk_fma_f32 v[6:7], v[148:149], v[70:71], v[6:7] op_sel_hi:[1,0,1]
	v_pk_fma_f32 v[4:5], v[150:151], v[50:51], v[4:5] op_sel_hi:[1,0,1]
	v_pk_fma_f32 v[2:3], v[148:149], v[50:51], v[2:3] op_sel_hi:[1,0,1]
	s_waitcnt vmcnt(10)
	v_pk_fma_f32 v[34:35], v[152:153], v[46:47], v[34:35] op_sel:[0,1,0]
	v_pk_fma_f32 v[36:37], v[154:155], v[46:47], v[36:37] op_sel:[0,1,0]
	v_pk_fma_f32 v[30:31], v[152:153], v[38:39], v[30:31] op_sel:[0,1,0]
	v_pk_fma_f32 v[32:33], v[154:155], v[38:39], v[32:33] op_sel:[0,1,0]
	v_pk_fma_f32 v[26:27], v[152:153], v[42:43], v[26:27] op_sel:[0,1,0]
	v_pk_fma_f32 v[28:29], v[154:155], v[42:43], v[28:29] op_sel:[0,1,0]
	v_pk_fma_f32 v[22:23], v[152:153], v[58:59], v[22:23] op_sel:[0,1,0]
	v_pk_fma_f32 v[24:25], v[154:155], v[58:59], v[24:25] op_sel:[0,1,0]
	v_pk_fma_f32 v[18:19], v[152:153], v[54:55], v[18:19] op_sel:[0,1,0]
	v_pk_fma_f32 v[20:21], v[154:155], v[54:55], v[20:21] op_sel:[0,1,0]
	v_pk_fma_f32 v[14:15], v[152:153], v[66:67], v[14:15] op_sel:[0,1,0]
	v_pk_fma_f32 v[16:17], v[154:155], v[66:67], v[16:17] op_sel:[0,1,0]
	v_pk_fma_f32 v[10:11], v[152:153], v[62:63], v[10:11] op_sel:[0,1,0]
	v_pk_fma_f32 v[12:13], v[154:155], v[62:63], v[12:13] op_sel:[0,1,0]
	v_pk_fma_f32 v[6:7], v[152:153], v[70:71], v[6:7] op_sel:[0,1,0]
	v_pk_fma_f32 v[8:9], v[154:155], v[70:71], v[8:9] op_sel:[0,1,0]
	v_pk_fma_f32 v[2:3], v[152:153], v[50:51], v[2:3] op_sel:[0,1,0]
	v_pk_fma_f32 v[4:5], v[154:155], v[50:51], v[4:5] op_sel:[0,1,0]
	s_waitcnt vmcnt(9)
	v_pk_fma_f32 v[36:37], v[158:159], v[48:49], v[36:37] op_sel_hi:[1,0,1]
	v_pk_fma_f32 v[34:35], v[156:157], v[48:49], v[34:35] op_sel_hi:[1,0,1]
	v_pk_fma_f32 v[32:33], v[158:159], v[40:41], v[32:33] op_sel_hi:[1,0,1]
	v_pk_fma_f32 v[30:31], v[156:157], v[40:41], v[30:31] op_sel_hi:[1,0,1]
	v_pk_fma_f32 v[28:29], v[158:159], v[44:45], v[28:29] op_sel_hi:[1,0,1]
	v_pk_fma_f32 v[26:27], v[156:157], v[44:45], v[26:27] op_sel_hi:[1,0,1]
	v_pk_fma_f32 v[24:25], v[158:159], v[60:61], v[24:25] op_sel_hi:[1,0,1]
	v_pk_fma_f32 v[22:23], v[156:157], v[60:61], v[22:23] op_sel_hi:[1,0,1]
	v_pk_fma_f32 v[20:21], v[158:159], v[56:57], v[20:21] op_sel_hi:[1,0,1]
	v_pk_fma_f32 v[18:19], v[156:157], v[56:57], v[18:19] op_sel_hi:[1,0,1]
	v_pk_fma_f32 v[16:17], v[158:159], v[68:69], v[16:17] op_sel_hi:[1,0,1]
	v_pk_fma_f32 v[14:15], v[156:157], v[68:69], v[14:15] op_sel_hi:[1,0,1]
	v_pk_fma_f32 v[12:13], v[158:159], v[64:65], v[12:13] op_sel_hi:[1,0,1]
	v_pk_fma_f32 v[10:11], v[156:157], v[64:65], v[10:11] op_sel_hi:[1,0,1]
	v_pk_fma_f32 v[8:9], v[158:159], v[72:73], v[8:9] op_sel_hi:[1,0,1]
	v_pk_fma_f32 v[6:7], v[156:157], v[72:73], v[6:7] op_sel_hi:[1,0,1]
	v_pk_fma_f32 v[4:5], v[158:159], v[52:53], v[4:5] op_sel_hi:[1,0,1]
	v_pk_fma_f32 v[2:3], v[156:157], v[52:53], v[2:3] op_sel_hi:[1,0,1]
	s_waitcnt vmcnt(8)
	v_pk_fma_f32 v[36:37], v[162:163], v[76:77], v[36:37] op_sel_hi:[1,0,1]
	v_pk_fma_f32 v[34:35], v[160:161], v[76:77], v[34:35] op_sel_hi:[1,0,1]
	v_pk_fma_f32 v[32:33], v[162:163], v[98:99], v[32:33] op_sel_hi:[1,0,1]
	v_pk_fma_f32 v[30:31], v[160:161], v[98:99], v[30:31] op_sel_hi:[1,0,1]
	v_pk_fma_f32 v[28:29], v[162:163], v[100:101], v[28:29] op_sel_hi:[1,0,1]
	v_pk_fma_f32 v[26:27], v[160:161], v[100:101], v[26:27] op_sel_hi:[1,0,1]
	v_pk_fma_f32 v[24:25], v[162:163], v[102:103], v[24:25] op_sel_hi:[1,0,1]
	v_pk_fma_f32 v[22:23], v[160:161], v[102:103], v[22:23] op_sel_hi:[1,0,1]
	v_pk_fma_f32 v[20:21], v[162:163], v[104:105], v[20:21] op_sel_hi:[1,0,1]
	v_pk_fma_f32 v[18:19], v[160:161], v[104:105], v[18:19] op_sel_hi:[1,0,1]
	v_pk_fma_f32 v[16:17], v[162:163], v[106:107], v[16:17] op_sel_hi:[1,0,1]
	v_pk_fma_f32 v[14:15], v[160:161], v[106:107], v[14:15] op_sel_hi:[1,0,1]
	v_pk_fma_f32 v[12:13], v[162:163], v[108:109], v[12:13] op_sel_hi:[1,0,1]
	v_pk_fma_f32 v[10:11], v[160:161], v[108:109], v[10:11] op_sel_hi:[1,0,1]
	v_pk_fma_f32 v[8:9], v[162:163], v[110:111], v[8:9] op_sel_hi:[1,0,1]
	v_pk_fma_f32 v[6:7], v[160:161], v[110:111], v[6:7] op_sel_hi:[1,0,1]
	v_pk_fma_f32 v[4:5], v[162:163], v[112:113], v[4:5] op_sel_hi:[1,0,1]
	v_pk_fma_f32 v[2:3], v[160:161], v[112:113], v[2:3] op_sel_hi:[1,0,1]
	ds_read_b128 v[38:41], v80 offset:4096
	ds_read_b128 v[42:45], v80 offset:8192
	ds_read_b128 v[46:49], v80
	ds_read_b128 v[50:53], v80 offset:32768
	ds_read_b128 v[58:61], v80 offset:12288
	ds_read_b128 v[54:57], v80 offset:16384
	ds_read_b128 v[66:69], v80 offset:20480
	ds_read_b128 v[62:65], v80 offset:24576
	ds_read_b128 v[70:73], v80 offset:28672
	s_waitcnt lgkmcnt(6)
	v_mov_b32_e32 v76, v49
	v_mov_b32_e32 v98, v41
	v_mov_b32_e32 v100, v45
	s_waitcnt lgkmcnt(4)
	v_mov_b32_e32 v102, v61
	s_waitcnt lgkmcnt(3)
	v_mov_b32_e32 v104, v57
	s_waitcnt lgkmcnt(2)
	v_mov_b32_e32 v106, v69
	s_waitcnt lgkmcnt(1)
	v_mov_b32_e32 v108, v65
	s_waitcnt lgkmcnt(0)
	v_mov_b32_e32 v110, v73
	v_mov_b32_e32 v112, v53
	v_add_u32_e32 v80, 16, v80
	s_waitcnt vmcnt(7)
	v_pk_fma_f32 v[36:37], v[166:167], v[46:47], v[36:37] op_sel_hi:[1,0,1]
	v_pk_fma_f32 v[34:35], v[164:165], v[46:47], v[34:35] op_sel_hi:[1,0,1]
	v_pk_fma_f32 v[32:33], v[166:167], v[38:39], v[32:33] op_sel_hi:[1,0,1]
	v_pk_fma_f32 v[30:31], v[164:165], v[38:39], v[30:31] op_sel_hi:[1,0,1]
	v_pk_fma_f32 v[28:29], v[166:167], v[42:43], v[28:29] op_sel_hi:[1,0,1]
	v_pk_fma_f32 v[26:27], v[164:165], v[42:43], v[26:27] op_sel_hi:[1,0,1]
	v_pk_fma_f32 v[24:25], v[166:167], v[58:59], v[24:25] op_sel_hi:[1,0,1]
	v_pk_fma_f32 v[22:23], v[164:165], v[58:59], v[22:23] op_sel_hi:[1,0,1]
	v_pk_fma_f32 v[20:21], v[166:167], v[54:55], v[20:21] op_sel_hi:[1,0,1]
	v_pk_fma_f32 v[18:19], v[164:165], v[54:55], v[18:19] op_sel_hi:[1,0,1]
	v_pk_fma_f32 v[16:17], v[166:167], v[66:67], v[16:17] op_sel_hi:[1,0,1]
	v_pk_fma_f32 v[14:15], v[164:165], v[66:67], v[14:15] op_sel_hi:[1,0,1]
	v_pk_fma_f32 v[12:13], v[166:167], v[62:63], v[12:13] op_sel_hi:[1,0,1]
	v_pk_fma_f32 v[10:11], v[164:165], v[62:63], v[10:11] op_sel_hi:[1,0,1]
	v_pk_fma_f32 v[8:9], v[166:167], v[70:71], v[8:9] op_sel_hi:[1,0,1]
	v_pk_fma_f32 v[6:7], v[164:165], v[70:71], v[6:7] op_sel_hi:[1,0,1]
	v_pk_fma_f32 v[4:5], v[166:167], v[50:51], v[4:5] op_sel_hi:[1,0,1]
	v_pk_fma_f32 v[2:3], v[164:165], v[50:51], v[2:3] op_sel_hi:[1,0,1]
	s_waitcnt vmcnt(6)
	v_pk_fma_f32 v[34:35], v[168:169], v[46:47], v[34:35] op_sel:[0,1,0]
	v_pk_fma_f32 v[36:37], v[170:171], v[46:47], v[36:37] op_sel:[0,1,0]
	v_pk_fma_f32 v[30:31], v[168:169], v[38:39], v[30:31] op_sel:[0,1,0]
	v_pk_fma_f32 v[32:33], v[170:171], v[38:39], v[32:33] op_sel:[0,1,0]
	v_pk_fma_f32 v[26:27], v[168:169], v[42:43], v[26:27] op_sel:[0,1,0]
	v_pk_fma_f32 v[28:29], v[170:171], v[42:43], v[28:29] op_sel:[0,1,0]
	v_pk_fma_f32 v[22:23], v[168:169], v[58:59], v[22:23] op_sel:[0,1,0]
	v_pk_fma_f32 v[24:25], v[170:171], v[58:59], v[24:25] op_sel:[0,1,0]
	v_pk_fma_f32 v[18:19], v[168:169], v[54:55], v[18:19] op_sel:[0,1,0]
	v_pk_fma_f32 v[20:21], v[170:171], v[54:55], v[20:21] op_sel:[0,1,0]
	v_pk_fma_f32 v[14:15], v[168:169], v[66:67], v[14:15] op_sel:[0,1,0]
	v_pk_fma_f32 v[16:17], v[170:171], v[66:67], v[16:17] op_sel:[0,1,0]
	v_pk_fma_f32 v[10:11], v[168:169], v[62:63], v[10:11] op_sel:[0,1,0]
	v_pk_fma_f32 v[12:13], v[170:171], v[62:63], v[12:13] op_sel:[0,1,0]
	v_pk_fma_f32 v[6:7], v[168:169], v[70:71], v[6:7] op_sel:[0,1,0]
	v_pk_fma_f32 v[8:9], v[170:171], v[70:71], v[8:9] op_sel:[0,1,0]
	v_pk_fma_f32 v[2:3], v[168:169], v[50:51], v[2:3] op_sel:[0,1,0]
	v_pk_fma_f32 v[4:5], v[170:171], v[50:51], v[4:5] op_sel:[0,1,0]
	s_waitcnt vmcnt(5)
	v_pk_fma_f32 v[36:37], v[174:175], v[48:49], v[36:37] op_sel_hi:[1,0,1]
	v_pk_fma_f32 v[34:35], v[172:173], v[48:49], v[34:35] op_sel_hi:[1,0,1]
	v_pk_fma_f32 v[32:33], v[174:175], v[40:41], v[32:33] op_sel_hi:[1,0,1]
	v_pk_fma_f32 v[30:31], v[172:173], v[40:41], v[30:31] op_sel_hi:[1,0,1]
	v_pk_fma_f32 v[28:29], v[174:175], v[44:45], v[28:29] op_sel_hi:[1,0,1]
	v_pk_fma_f32 v[26:27], v[172:173], v[44:45], v[26:27] op_sel_hi:[1,0,1]
	v_pk_fma_f32 v[24:25], v[174:175], v[60:61], v[24:25] op_sel_hi:[1,0,1]
	v_pk_fma_f32 v[22:23], v[172:173], v[60:61], v[22:23] op_sel_hi:[1,0,1]
	v_pk_fma_f32 v[20:21], v[174:175], v[56:57], v[20:21] op_sel_hi:[1,0,1]
	v_pk_fma_f32 v[18:19], v[172:173], v[56:57], v[18:19] op_sel_hi:[1,0,1]
	v_pk_fma_f32 v[16:17], v[174:175], v[68:69], v[16:17] op_sel_hi:[1,0,1]
	v_pk_fma_f32 v[14:15], v[172:173], v[68:69], v[14:15] op_sel_hi:[1,0,1]
	v_pk_fma_f32 v[12:13], v[174:175], v[64:65], v[12:13] op_sel_hi:[1,0,1]
	v_pk_fma_f32 v[10:11], v[172:173], v[64:65], v[10:11] op_sel_hi:[1,0,1]
	v_pk_fma_f32 v[8:9], v[174:175], v[72:73], v[8:9] op_sel_hi:[1,0,1]
	v_pk_fma_f32 v[6:7], v[172:173], v[72:73], v[6:7] op_sel_hi:[1,0,1]
	v_pk_fma_f32 v[4:5], v[174:175], v[52:53], v[4:5] op_sel_hi:[1,0,1]
	v_pk_fma_f32 v[2:3], v[172:173], v[52:53], v[2:3] op_sel_hi:[1,0,1]
	s_waitcnt vmcnt(4)
	v_pk_fma_f32 v[36:37], v[178:179], v[76:77], v[36:37] op_sel_hi:[1,0,1]
	v_pk_fma_f32 v[34:35], v[176:177], v[76:77], v[34:35] op_sel_hi:[1,0,1]
	v_pk_fma_f32 v[32:33], v[178:179], v[98:99], v[32:33] op_sel_hi:[1,0,1]
	v_pk_fma_f32 v[30:31], v[176:177], v[98:99], v[30:31] op_sel_hi:[1,0,1]
	v_pk_fma_f32 v[28:29], v[178:179], v[100:101], v[28:29] op_sel_hi:[1,0,1]
	v_pk_fma_f32 v[26:27], v[176:177], v[100:101], v[26:27] op_sel_hi:[1,0,1]
	v_pk_fma_f32 v[24:25], v[178:179], v[102:103], v[24:25] op_sel_hi:[1,0,1]
	v_pk_fma_f32 v[22:23], v[176:177], v[102:103], v[22:23] op_sel_hi:[1,0,1]
	v_pk_fma_f32 v[20:21], v[178:179], v[104:105], v[20:21] op_sel_hi:[1,0,1]
	v_pk_fma_f32 v[18:19], v[176:177], v[104:105], v[18:19] op_sel_hi:[1,0,1]
	v_pk_fma_f32 v[16:17], v[178:179], v[106:107], v[16:17] op_sel_hi:[1,0,1]
	v_pk_fma_f32 v[14:15], v[176:177], v[106:107], v[14:15] op_sel_hi:[1,0,1]
	v_pk_fma_f32 v[12:13], v[178:179], v[108:109], v[12:13] op_sel_hi:[1,0,1]
	v_pk_fma_f32 v[10:11], v[176:177], v[108:109], v[10:11] op_sel_hi:[1,0,1]
	v_pk_fma_f32 v[8:9], v[178:179], v[110:111], v[8:9] op_sel_hi:[1,0,1]
	v_pk_fma_f32 v[6:7], v[176:177], v[110:111], v[6:7] op_sel_hi:[1,0,1]
	v_pk_fma_f32 v[4:5], v[178:179], v[112:113], v[4:5] op_sel_hi:[1,0,1]
	v_pk_fma_f32 v[2:3], v[176:177], v[112:113], v[2:3] op_sel_hi:[1,0,1]
	ds_read_b128 v[38:41], v80 offset:4096
	ds_read_b128 v[42:45], v80 offset:8192
	ds_read_b128 v[46:49], v80
	ds_read_b128 v[50:53], v80 offset:32768
	ds_read_b128 v[58:61], v80 offset:12288
	ds_read_b128 v[54:57], v80 offset:16384
	ds_read_b128 v[66:69], v80 offset:20480
	ds_read_b128 v[62:65], v80 offset:24576
	ds_read_b128 v[70:73], v80 offset:28672
	s_waitcnt lgkmcnt(6)
	v_mov_b32_e32 v76, v49
	v_mov_b32_e32 v98, v41
	v_mov_b32_e32 v100, v45
	s_waitcnt lgkmcnt(4)
	v_mov_b32_e32 v102, v61
	s_waitcnt lgkmcnt(3)
	v_mov_b32_e32 v104, v57
	s_waitcnt lgkmcnt(2)
	v_mov_b32_e32 v106, v69
	s_waitcnt lgkmcnt(1)
	v_mov_b32_e32 v108, v65
	s_waitcnt lgkmcnt(0)
	v_mov_b32_e32 v110, v73
	v_mov_b32_e32 v112, v53
	v_add_u32_e32 v80, 16, v80
	s_waitcnt vmcnt(3)
	v_pk_fma_f32 v[36:37], v[182:183], v[46:47], v[36:37] op_sel_hi:[1,0,1]
	v_pk_fma_f32 v[34:35], v[180:181], v[46:47], v[34:35] op_sel_hi:[1,0,1]
	v_pk_fma_f32 v[32:33], v[182:183], v[38:39], v[32:33] op_sel_hi:[1,0,1]
	v_pk_fma_f32 v[30:31], v[180:181], v[38:39], v[30:31] op_sel_hi:[1,0,1]
	v_pk_fma_f32 v[28:29], v[182:183], v[42:43], v[28:29] op_sel_hi:[1,0,1]
	v_pk_fma_f32 v[26:27], v[180:181], v[42:43], v[26:27] op_sel_hi:[1,0,1]
	v_pk_fma_f32 v[24:25], v[182:183], v[58:59], v[24:25] op_sel_hi:[1,0,1]
	v_pk_fma_f32 v[22:23], v[180:181], v[58:59], v[22:23] op_sel_hi:[1,0,1]
	v_pk_fma_f32 v[20:21], v[182:183], v[54:55], v[20:21] op_sel_hi:[1,0,1]
	v_pk_fma_f32 v[18:19], v[180:181], v[54:55], v[18:19] op_sel_hi:[1,0,1]
	v_pk_fma_f32 v[16:17], v[182:183], v[66:67], v[16:17] op_sel_hi:[1,0,1]
	v_pk_fma_f32 v[14:15], v[180:181], v[66:67], v[14:15] op_sel_hi:[1,0,1]
	v_pk_fma_f32 v[12:13], v[182:183], v[62:63], v[12:13] op_sel_hi:[1,0,1]
	v_pk_fma_f32 v[10:11], v[180:181], v[62:63], v[10:11] op_sel_hi:[1,0,1]
	v_pk_fma_f32 v[8:9], v[182:183], v[70:71], v[8:9] op_sel_hi:[1,0,1]
	v_pk_fma_f32 v[6:7], v[180:181], v[70:71], v[6:7] op_sel_hi:[1,0,1]
	v_pk_fma_f32 v[4:5], v[182:183], v[50:51], v[4:5] op_sel_hi:[1,0,1]
	v_pk_fma_f32 v[2:3], v[180:181], v[50:51], v[2:3] op_sel_hi:[1,0,1]
	s_waitcnt vmcnt(2)
	v_pk_fma_f32 v[34:35], v[184:185], v[46:47], v[34:35] op_sel:[0,1,0]
	v_pk_fma_f32 v[36:37], v[186:187], v[46:47], v[36:37] op_sel:[0,1,0]
	v_pk_fma_f32 v[30:31], v[184:185], v[38:39], v[30:31] op_sel:[0,1,0]
	v_pk_fma_f32 v[32:33], v[186:187], v[38:39], v[32:33] op_sel:[0,1,0]
	v_pk_fma_f32 v[26:27], v[184:185], v[42:43], v[26:27] op_sel:[0,1,0]
	v_pk_fma_f32 v[28:29], v[186:187], v[42:43], v[28:29] op_sel:[0,1,0]
	v_pk_fma_f32 v[22:23], v[184:185], v[58:59], v[22:23] op_sel:[0,1,0]
	v_pk_fma_f32 v[24:25], v[186:187], v[58:59], v[24:25] op_sel:[0,1,0]
	v_pk_fma_f32 v[18:19], v[184:185], v[54:55], v[18:19] op_sel:[0,1,0]
	v_pk_fma_f32 v[20:21], v[186:187], v[54:55], v[20:21] op_sel:[0,1,0]
	v_pk_fma_f32 v[14:15], v[184:185], v[66:67], v[14:15] op_sel:[0,1,0]
	v_pk_fma_f32 v[16:17], v[186:187], v[66:67], v[16:17] op_sel:[0,1,0]
	v_pk_fma_f32 v[10:11], v[184:185], v[62:63], v[10:11] op_sel:[0,1,0]
	v_pk_fma_f32 v[12:13], v[186:187], v[62:63], v[12:13] op_sel:[0,1,0]
	v_pk_fma_f32 v[6:7], v[184:185], v[70:71], v[6:7] op_sel:[0,1,0]
	v_pk_fma_f32 v[8:9], v[186:187], v[70:71], v[8:9] op_sel:[0,1,0]
	v_pk_fma_f32 v[2:3], v[184:185], v[50:51], v[2:3] op_sel:[0,1,0]
	v_pk_fma_f32 v[4:5], v[186:187], v[50:51], v[4:5] op_sel:[0,1,0]
	s_waitcnt vmcnt(1)
	v_pk_fma_f32 v[36:37], v[190:191], v[48:49], v[36:37] op_sel_hi:[1,0,1]
	v_pk_fma_f32 v[34:35], v[188:189], v[48:49], v[34:35] op_sel_hi:[1,0,1]
	v_pk_fma_f32 v[32:33], v[190:191], v[40:41], v[32:33] op_sel_hi:[1,0,1]
	v_pk_fma_f32 v[30:31], v[188:189], v[40:41], v[30:31] op_sel_hi:[1,0,1]
	v_pk_fma_f32 v[28:29], v[190:191], v[44:45], v[28:29] op_sel_hi:[1,0,1]
	v_pk_fma_f32 v[26:27], v[188:189], v[44:45], v[26:27] op_sel_hi:[1,0,1]
	v_pk_fma_f32 v[24:25], v[190:191], v[60:61], v[24:25] op_sel_hi:[1,0,1]
	v_pk_fma_f32 v[22:23], v[188:189], v[60:61], v[22:23] op_sel_hi:[1,0,1]
	v_pk_fma_f32 v[20:21], v[190:191], v[56:57], v[20:21] op_sel_hi:[1,0,1]
	v_pk_fma_f32 v[18:19], v[188:189], v[56:57], v[18:19] op_sel_hi:[1,0,1]
	v_pk_fma_f32 v[16:17], v[190:191], v[68:69], v[16:17] op_sel_hi:[1,0,1]
	v_pk_fma_f32 v[14:15], v[188:189], v[68:69], v[14:15] op_sel_hi:[1,0,1]
	v_pk_fma_f32 v[12:13], v[190:191], v[64:65], v[12:13] op_sel_hi:[1,0,1]
	v_pk_fma_f32 v[10:11], v[188:189], v[64:65], v[10:11] op_sel_hi:[1,0,1]
	v_pk_fma_f32 v[8:9], v[190:191], v[72:73], v[8:9] op_sel_hi:[1,0,1]
	v_pk_fma_f32 v[6:7], v[188:189], v[72:73], v[6:7] op_sel_hi:[1,0,1]
	v_pk_fma_f32 v[4:5], v[190:191], v[52:53], v[4:5] op_sel_hi:[1,0,1]
	v_pk_fma_f32 v[2:3], v[188:189], v[52:53], v[2:3] op_sel_hi:[1,0,1]
	s_waitcnt vmcnt(0)
	v_pk_fma_f32 v[36:37], v[194:195], v[76:77], v[36:37] op_sel_hi:[1,0,1]
	v_pk_fma_f32 v[34:35], v[192:193], v[76:77], v[34:35] op_sel_hi:[1,0,1]
	v_pk_fma_f32 v[32:33], v[194:195], v[98:99], v[32:33] op_sel_hi:[1,0,1]
	v_pk_fma_f32 v[30:31], v[192:193], v[98:99], v[30:31] op_sel_hi:[1,0,1]
	v_pk_fma_f32 v[28:29], v[194:195], v[100:101], v[28:29] op_sel_hi:[1,0,1]
	v_pk_fma_f32 v[26:27], v[192:193], v[100:101], v[26:27] op_sel_hi:[1,0,1]
	v_pk_fma_f32 v[24:25], v[194:195], v[102:103], v[24:25] op_sel_hi:[1,0,1]
	v_pk_fma_f32 v[22:23], v[192:193], v[102:103], v[22:23] op_sel_hi:[1,0,1]
	v_pk_fma_f32 v[20:21], v[194:195], v[104:105], v[20:21] op_sel_hi:[1,0,1]
	v_pk_fma_f32 v[18:19], v[192:193], v[104:105], v[18:19] op_sel_hi:[1,0,1]
	v_pk_fma_f32 v[16:17], v[194:195], v[106:107], v[16:17] op_sel_hi:[1,0,1]
	v_pk_fma_f32 v[14:15], v[192:193], v[106:107], v[14:15] op_sel_hi:[1,0,1]
	v_pk_fma_f32 v[12:13], v[194:195], v[108:109], v[12:13] op_sel_hi:[1,0,1]
	v_pk_fma_f32 v[10:11], v[192:193], v[108:109], v[10:11] op_sel_hi:[1,0,1]
	v_pk_fma_f32 v[8:9], v[194:195], v[110:111], v[8:9] op_sel_hi:[1,0,1]
	v_pk_fma_f32 v[6:7], v[192:193], v[110:111], v[6:7] op_sel_hi:[1,0,1]
	v_pk_fma_f32 v[4:5], v[194:195], v[112:113], v[4:5] op_sel_hi:[1,0,1]
	v_pk_fma_f32 v[2:3], v[192:193], v[112:113], v[2:3] op_sel_hi:[1,0,1]
	v_and_b32_e32 v38, 0x7c, v79
	s_movk_i32 s5, 0x1200
	v_lshlrev_b32_e32 v38, 2, v38
	v_mul_lo_u32 v0, v0, s5
	s_movk_i32 s5, 0x480
	v_add3_u32 v0, 0, v38, v0
	v_cmp_gt_i32_e32 vcc, s5, v78
	ds_write_b128 v0, v[34:37] offset:36864
	ds_write_b128 v0, v[30:33] offset:37376
	ds_write_b128 v0, v[26:29] offset:37888
	ds_write_b128 v0, v[22:25] offset:38400
	ds_write_b128 v0, v[18:21] offset:38912
	ds_write_b128 v0, v[14:17] offset:39424
	ds_write_b128 v0, v[10:13] offset:39936
	ds_write_b128 v0, v[6:9] offset:40448
	ds_write_b128 v0, v[2:5] offset:40960
	s_waitcnt lgkmcnt(0)
	s_barrier
	s_and_saveexec_b64 s[6:7], vcc
	s_cbranch_execz .LBB0_1521
	s_mul_i32 s5, s3, 0x1800
	s_add_i32 s5, s5, s4
	s_and_b32 s4, s4, 0x380
	v_and_b32_e32 v0, 0x7f, v78
	v_or_b32_e32 v2, s5, v0
	v_readlane_b32 s24, v253, 58
	v_lshl_add_u32 v6, v0, 2, 0
	v_or_b32_e32 v0, s4, v0
	s_ashr_i32 s20, s10, 3
	v_ashrrev_i32_e32 v3, 31, v2
	v_readlane_b32 s26, v253, 60
	v_readlane_b32 s27, v253, 61
	v_lshlrev_b32_e32 v0, 2, v0
	s_mul_i32 s3, s3, 9
	s_ashr_i32 s21, s20, 31
	v_lshl_add_u64 v[2:3], v[2:3], 2, s[26:27]
	v_lshl_add_u64 v[4:5], s[58:59], 0, v[0:1]
	s_mov_b64 s[4:5], 0
	v_readlane_b32 s25, v253, 59
